# v18 + attention item set-up: gate tile wait/LDS-write ladder moved behind the address set-up
# speedup vs baseline: 1.0171x; 1.0082x over previous
; template <int PM> DI void attn_phase(const Params& p, int l, char* smem, int* s_item, int wv, int cidx) {
;     ...
;     int qoff, koff, voff;
;     if (mixer == 0) { qoff = head * 128; koff = 512 + head * 128; voff = 1024 + head * 128; }
;     else if (mixer == 1) { qoff = 1536 + head * 128; koff = 2048 + (head >> 1) * 128; voff = 2304 + (head >> 1) * 128; }
;     else if (mixer == 2) { qoff = 2560 + head * 128; koff = 3072 + head * 128; voff = 3584 + head * 128; }
;     else { qoff = 4096 + head * 128; koff = 4608 + (head >> 1) * 128; voff = 4864 + (head >> 1) * 128; }
;     const int Rb = b * TPB;
;     const int Rq = Rb + (isctx ? 0 : 256) + qt * 256 + w * 32 + l31;
;     int nplain, nlocal = 0, local_t0 = 0, mode = 0;
;     if (isctx) nplain = 4;
;     else if (mixer == 0 || mixer == 3) nplain = 36;
;     else if (mixer == 1) {
;       nplain = 4; mode = 1;
;       const int ts = max(0, qt * 256 - 128), te = min(2048, qt * 256 + 384);
;       local_t0 = ts; nlocal = (te - ts) >> 6;
;     } else {
;       nplain = 4; mode = 2;
;       const int r0 = 4 * qt;
;       const int lo = min(max(r0 - 4, 0), 24), hi = min(max(r0 - 1, 0), 24) + 8;
;       local_t0 = lo * 64; nlocal = hi - lo;
;     }
;     const int ntl = nplain + nlocal;
;     const int tq0 = qt * 256 + w * 32;
;     const int tq = tq0 + l31;
;     const int qrow = tq0 >> 6, qcol = tq & 63;
;     const int kr0 = min(max(qrow - 4, 0), 24);
;     const int cstart = min(max(qcol - 8, 0), 48);
;     if (mode == 2) {
;       if (tid < 465) rpb_s[tid] = p.rpb[(l * 4 + head) * 465 + tid] * LOG2E;
;     }
;     {
;       const u16* gsrc = p.P + (size_t)(Rb + (isctx ? 0 : 256) + qt * 256 + (tid >> 4)) * INW + 5120 + mixer * 512 + head * 128 + (tid & 15) * 8;
;       u32x4 gt[8];
; #pragma unroll
;       for (int j = 0; j < 8; ++j) gt[j] = *(const u32x4*)(gsrc + (size_t)j * 32 * INW);
; #pragma unroll
;       for (int j = 0; j < 8; ++j) *(u32x4*)(gate_s + ((tid >> 4) + 32 * j) * 264 + (tid & 15) * 16) = gt[j];
;     }
.LBB0_406:
	s_or_b64 exec, exec, s[2:3]
	v_readlane_b32 s2, v254, 57
	s_add_i32 s88, s18, s2
	s_ashr_i32 s82, s88, 6
	s_max_i32 s2, s82, 4
	s_add_i32 s2, s2, -4
	s_xor_b64 s[78:79], s[14:15], -1
	s_add_i32 s81, s80, s11
	s_min_u32 s83, s2, 24
	s_and_b32 s84, s7, 3
	s_and_b64 s[0:1], exec, s[0:1]
	s_cselect_b32 s0, 0, 0x100
	s_mulk_i32 s84, 0x900
	s_add_i32 s0, s18, s0
	v_readlane_b32 s36, v253, 21
	s_add_i32 s2, s0, s84
	v_readlane_b32 s50, v253, 35
	v_readlane_b32 s51, v253, 36
	v_add_u32_e32 v0, s2, v239
	s_movk_i32 s22, 0x3800
	v_mov_b64_e32 v[14:15], s[50:51]
	v_mad_i64_i32 v[2:3], s[0:1], v0, s22, v[14:15]
	s_mov_b32 s17, s21
	s_lshl_b32 s16, s86, 10
	v_lshl_add_u64 v[2:3], v[2:3], 0, s[16:17]
	s_lshl_b32 s0, s20, 1
	s_mov_b32 s1, s21
	v_lshl_add_u64 v[2:3], v[2:3], 0, s[0:1]
	v_mov_b32_e32 v205, v1
	v_lshl_add_u64 v[60:61], v[2:3], 0, v[204:205]
	s_movk_i32 s3, 0x2000
	v_add_co_u32_e32 v2, vcc, s3, v60
	s_mov_b32 s3, 0x72000
	s_nop 0
	v_addc_co_u32_e32 v3, vcc, 0, v61, vcc
	v_add_co_u32_e32 v6, vcc, s3, v60
	s_mov_b32 s3, 0xe2000
	s_nop 0
	v_addc_co_u32_e32 v7, vcc, 0, v61, vcc
	v_add_co_u32_e32 v10, vcc, s3, v60
	s_mov_b32 s3, 0x152000
	s_nop 0
	v_addc_co_u32_e32 v11, vcc, 0, v61, vcc
	v_add_co_u32_e32 v48, vcc, s3, v60
	s_mov_b32 s3, 0x1c2000
	s_nop 0
	v_addc_co_u32_e32 v49, vcc, 0, v61, vcc
	v_add_co_u32_e32 v52, vcc, s3, v60
	s_mov_b32 s3, 0x232000
	s_nop 0
	v_addc_co_u32_e32 v53, vcc, 0, v61, vcc
	v_add_co_u32_e32 v56, vcc, s3, v60
	s_mov_b32 s3, 0x2a2000
	s_nop 0
	v_addc_co_u32_e32 v57, vcc, 0, v61, vcc
	v_add_co_u32_e32 v62, vcc, s3, v60
	s_mov_b32 s3, 0x312000
	s_nop 0
	v_addc_co_u32_e32 v63, vcc, 0, v61, vcc
	v_add_co_u32_e32 v64, vcc, s3, v60
	global_load_dwordx4 v[16:19], v[2:3], off offset:2048
	s_nop 0
	global_load_dwordx4 v[20:23], v[6:7], off offset:2048
	v_addc_co_u32_e32 v65, vcc, 0, v61, vcc
	global_load_dwordx4 v[24:27], v[10:11], off offset:2048
	s_nop 0
	global_load_dwordx4 v[28:31], v[48:49], off offset:2048
	s_nop 0
	global_load_dwordx4 v[32:35], v[52:53], off offset:2048
	s_nop 0
	global_load_dwordx4 v[36:39], v[56:57], off offset:2048
	s_nop 0
	global_load_dwordx4 v[40:43], v[62:63], off offset:2048
	s_nop 0
	global_load_dwordx4 v[44:47], v[64:65], off offset:2048
	v_readlane_b32 s14, v254, 61
	v_readlane_b32 s15, v254, 62
	s_and_b64 s[14:15], s[14:15], exec
	v_add_u32_e32 v68, s2, v241
	s_cselect_b32 s13, 2, 1
	s_lshl_b32 s2, s20, 2
	v_ashrrev_i32_e32 v69, 31, v68
	s_cmp_gt_i32 s81, 1
	v_lshlrev_b64 v[70:71], 11, v[68:69]
	s_cselect_b64 s[14:15], -1, 0
	s_mov_b32 s3, s21
	v_lshl_add_u64 v[70:71], s[92:93], 0, v[70:71]
	v_writelane_b32 v255, s14, 1
	s_cmp_gt_i32 s81, 0
	v_lshl_add_u64 v[70:71], v[70:71], 0, s[2:3]
	v_writelane_b32 v255, s15, 2
	s_cselect_b64 s[2:3], -1, 0
	v_writelane_b32 v255, s2, 3
	v_bitop3_b32 v205, s88, 63, v240 bitop3:0xc8
	v_sub_u32_e64 v0, v205, 8 clamp
	v_writelane_b32 v255, s3, 4
	s_add_i32 s2, s13, -1
	v_writelane_b32 v255, s13, 5
	s_cmp_eq_u32 s86, 1
	v_min_u32_e32 v0, 48, v0
	v_writelane_b32 v255, s2, 6
	s_cselect_b64 s[2:3], -1, 0
	s_mov_b32 s7, s21
	v_writelane_b32 v255, s2, 7
	s_mov_b32 s9, s21
	s_lshl_b64 s[96:97], s[6:7], 1
	v_writelane_b32 v255, s3, 8
	v_readlane_b32 s37, v253, 22
	v_readlane_b32 s38, v253, 23
	v_readlane_b32 s39, v253, 24
	v_readlane_b32 s40, v253, 25
	v_readlane_b32 s41, v253, 26
	v_sub_u32_e32 v6, v198, v0
	v_mad_i64_i32 v[4:5], s[2:3], v68, s22, v[14:15]
	v_cmp_gt_u32_e64 s[6:7], 16, v6
	v_sub_u32_e32 v6, v248, v0
	v_lshl_add_u64 v[4:5], s[8:9], 1, v[4:5]
	v_cmp_gt_u32_e64 s[8:9], 16, v6
	v_add_u32_e32 v6, 8, v198
	v_sub_u32_e32 v10, v6, v0
	v_add_u32_e32 v6, 9, v198
	v_sub_u32_e32 v11, v6, v0
	v_add_u32_e32 v6, 10, v198
	v_sub_u32_e32 v12, v6, v0
	v_add_u32_e32 v6, 11, v198
	v_sub_u32_e32 v13, v6, v0
	v_add_u32_e32 v6, 16, v198
	v_sub_u32_e32 v14, v6, v0
	v_add_u32_e32 v6, 17, v198
	v_sub_u32_e32 v15, v6, v0
	v_add_u32_e32 v6, 18, v198
	v_sub_u32_e32 v48, v6, v0
	v_add_u32_e32 v6, 19, v198
	v_sub_u32_e32 v49, v6, v0
	v_add_u32_e32 v6, 24, v198
	v_sub_u32_e32 v50, v6, v0
	v_add_u32_e32 v6, 25, v198
	v_sub_u32_e32 v51, v6, v0
	v_add_u32_e32 v6, 26, v198
	v_sub_u32_e32 v52, v6, v0
	v_add_u32_e32 v6, 27, v198
	v_sub_u32_e32 v53, v6, v0
	v_add_u32_e32 v6, 32, v198
	v_sub_u32_e32 v54, v6, v0
	v_add_u32_e32 v6, 33, v198
	v_sub_u32_e32 v55, v6, v0
	v_add_u32_e32 v6, 34, v198
	v_sub_u32_e32 v56, v6, v0
	v_add_u32_e32 v6, 35, v198
	v_readlane_b32 s42, v253, 27
	v_readlane_b32 s43, v253, 28
	v_readlane_b32 s44, v253, 29
; template <int PM> DI void attn_phase(const Params& p, int l, char* smem, int* s_item, int wv, int cidx) {
;     ...
;         const u16* base = p.P + (size_t)(Rb + trow) * INW + tch * 8;
; #pragma unroll
;         for (int j = 0; j < 2; ++j) {
;           kst[j] = *(const u32x4*)(base + (size_t)j * 32 * INW + koff);
;           vst[j] = *(const u32x4*)(base + (size_t)j * 32 * INW + voff);
;         }
; #pragma unroll
;         for (int j = 0; j < 2; ++j) {
;           *(u32x4*)(Kb0 + (trow + 32 * j) * 272 + tch * 16) = kst[j];
;           *(u32x4*)(Vb0 + (trow + 32 * j) * 320 + tch * 16) = vst[j];
;         }
;         const int R1 = (1 < nplain) ? Rb + 64 : Rb + 256 + local_t0 + 64 * (1 - nplain);
;         const u16* b1 = p.P + (size_t)(R1 + trow) * INW + tch * 8;
;     ...
;                   const int kidx = kb * 32 + (e & 3) + 8 * (e >> 2) + 4 * h;
;                   const int dc = kidx - cstart;
;                   const bool valid = dc >= 0 && dc < 16;
	v_readlane_b32 s45, v253, 30
	v_readlane_b32 s46, v253, 31
	v_readlane_b32 s47, v253, 32
	v_readlane_b32 s48, v253, 33
	v_readlane_b32 s49, v253, 34
	v_sub_u32_e32 v57, v6, v0
	v_add_u32_e32 v6, 40, v198
	s_mov_b32 s11, s21
	s_ashr_i32 s13, s12, 31
	v_readlane_b32 s36, v253, 5
	v_sub_u32_e32 v58, v6, v0
	v_add_u32_e32 v6, 41, v198
	s_add_i32 s87, s88, 0xffffff80
	s_addk_i32 s88, 0x9f
	s_lshl_b64 s[76:77], s[10:11], 1
	s_lshl_b64 s[2:3], s[12:13], 2
	v_readlane_b32 s46, v253, 15
	v_sub_u32_e32 v59, v6, v0
	v_add_u32_e32 v6, 42, v198
	v_readlane_b32 s47, v253, 16
	s_add_u32 s2, s46, s2
	v_sub_u32_e32 v60, v6, v0
	v_add_u32_e32 v6, 43, v198
	s_addc_u32 s3, s47, s3
	v_sub_u32_e32 v61, v6, v0
	v_add_u32_e32 v6, 48, v198
	v_lshlrev_b64 v[2:3], 12, v[68:69]
	v_writelane_b32 v255, s2, 9
	v_sub_u32_e32 v62, v6, v0
	v_add_u32_e32 v6, 49, v198
	v_writelane_b32 v255, s3, 10
	v_lshl_add_u64 v[2:3], s[56:57], 0, v[2:3]
	s_mov_b32 s3, s21
	v_sub_u32_e32 v63, v6, v0
	v_add_u32_e32 v6, 50, v198
	v_add_u32_e32 v72, s84, v239
	v_writelane_b32 v254, s2, 59
	v_lshl_add_u64 v[2:3], v[2:3], 0, s[16:17]
	v_sub_u32_e32 v64, v6, v0
	v_add_u32_e32 v6, 51, v198
	v_writelane_b32 v254, s3, 60
	v_lshl_add_u64 v[2:3], v[2:3], 0, s[0:1]
	v_sub_u32_e32 v65, v6, v0
	v_add_u32_e32 v6, 56, v198
	v_lshl_add_u64 v[208:209], v[200:201], 1, v[4:5]
	v_mad_i64_i32 v[4:5], s[0:1], v72, s22, v[202:203]
	s_mov_b64 s[2:3], 0x70000
	v_add_u32_e32 v73, 64, v72
	v_sub_u32_e32 v66, v6, v0
	v_add_u32_e32 v6, 57, v198
	v_lshl_add_u64 v[210:211], v[4:5], 0, s[96:97]
	v_lshl_add_u64 v[212:213], v[4:5], 0, s[76:77]
	v_lshl_add_u64 v[4:5], v[4:5], 0, s[2:3]
	v_sub_u32_e32 v67, v6, v0
	v_add_u32_e32 v6, 58, v198
	v_lshl_add_u64 v[214:215], v[4:5], 0, s[96:97]
	v_lshl_add_u64 v[216:217], v[4:5], 0, s[76:77]
	v_mad_i64_i32 v[4:5], s[0:1], v73, s22, v[202:203]
	v_sub_u32_e32 v68, v6, v0
	v_add_u32_e32 v6, 59, v198
	s_lshl_b32 s0, s80, 6
	v_readlane_b32 s37, v253, 6
	v_readlane_b32 s38, v253, 7
	v_readlane_b32 s39, v253, 8
	v_readlane_b32 s40, v253, 9
	v_readlane_b32 s41, v253, 10
	v_readlane_b32 s42, v253, 11
	v_readlane_b32 s43, v253, 12
	v_readlane_b32 s44, v253, 13
	v_readlane_b32 s45, v253, 14
	v_readlane_b32 s48, v253, 17
	v_readlane_b32 s49, v253, 18
	v_readlane_b32 s50, v253, 19
	v_readlane_b32 s51, v253, 20
	v_sub_u32_e32 v8, v249, v0
	v_sub_u32_e32 v9, v250, v0
	v_sub_u32_e32 v0, v6, v0
	v_lshl_add_u64 v[6:7], v[4:5], 0, s[2:3]
	s_sub_i32 s0, s19, s0
	v_lshl_add_u64 v[206:207], v[198:199], 2, v[70:71]
	s_movk_i32 s85, 0x3800
	s_mov_b64 s[98:99], 0x70000
	v_lshl_add_u64 v[218:219], v[6:7], 0, s[76:77]
	v_lshl_add_u64 v[220:221], v[6:7], 0, s[96:97]
	v_lshl_add_u64 v[222:223], v[4:5], 0, s[76:77]
	v_lshl_add_u64 v[224:225], v[4:5], 0, s[96:97]
	v_lshl_add_u64 v[226:227], v[198:199], 1, v[2:3]
	v_writelane_b32 v255, s0, 11
	v_subrev_u32_e32 v228, s18, v197
	s_add_i32 s90, s84, 0x180
	v_mov_b32_e32 v229, 0
	s_mov_b32 s91, 0
	v_cmp_gt_u32_e64 s[10:11], 16, v8
	v_cmp_gt_u32_e64 s[12:13], 16, v9
	v_cmp_gt_u32_e64 s[14:15], 16, v10
	v_cmp_gt_u32_e64 s[16:17], 16, v11
	v_cmp_gt_u32_e64 s[18:19], 16, v12
	v_cmp_gt_u32_e64 s[20:21], 16, v13
	v_cmp_gt_u32_e64 s[22:23], 16, v14
	v_cmp_gt_u32_e64 s[24:25], 16, v15
	v_cmp_gt_u32_e64 s[26:27], 16, v48
	v_cmp_gt_u32_e64 s[28:29], 16, v49
	v_cmp_gt_u32_e64 s[30:31], 16, v50
	v_cmp_gt_u32_e64 s[34:35], 16, v51
	v_cmp_gt_u32_e64 s[36:37], 16, v52
	v_cmp_gt_u32_e64 s[38:39], 16, v53
	v_cmp_gt_u32_e64 s[40:41], 16, v54
	v_cmp_gt_u32_e64 s[42:43], 16, v55
	v_cmp_gt_u32_e64 s[44:45], 16, v56
	v_cmp_gt_u32_e64 s[46:47], 16, v57
	v_cmp_gt_u32_e64 s[48:49], 16, v58
	v_cmp_gt_u32_e64 s[50:51], 16, v59
	v_cmp_gt_u32_e64 s[52:53], 16, v60
	v_cmp_gt_u32_e64 s[54:55], 16, v61
	v_cmp_gt_u32_e64 s[56:57], 16, v62
	v_cmp_gt_u32_e64 s[58:59], 16, v63
	v_cmp_gt_u32_e64 s[60:61], 16, v64
	v_cmp_gt_u32_e64 s[62:63], 16, v65
	v_cmp_gt_u32_e64 s[64:65], 16, v66
	v_cmp_gt_u32_e64 s[66:67], 16, v67
	v_cmp_gt_u32_e64 s[68:69], 16, v68
	v_cmp_gt_u32_e64 s[70:71], 16, v0
	s_waitcnt vmcnt(7)
	ds_write_b128 v251, v[16:19]
	s_waitcnt vmcnt(6)
	ds_write_b128 v251, v[20:23] offset:8448
	s_waitcnt vmcnt(5)
	ds_write_b128 v251, v[24:27] offset:16896
	s_waitcnt vmcnt(4)
	ds_write_b128 v251, v[28:31] offset:25344
	s_waitcnt vmcnt(3)
	ds_write_b128 v251, v[32:35] offset:33792
	s_waitcnt vmcnt(2)
	ds_write_b128 v251, v[36:39] offset:42240
	s_waitcnt vmcnt(1)
	ds_write_b128 v251, v[40:43] offset:50688
	s_waitcnt vmcnt(0)
	ds_write_b128 v251, v[44:47] offset:59136
	s_branch .LBB0_409
